# t15 + XCD leader no longer adds to the (now unread) per-XCD generation word next to its acquire
# baseline (speedup 1.0000x reference)
.LBB0_408:
	s_or_b64 exec, exec, s[0:1]
	s_add_i32 s0, s22, 0x900
	s_mov_b32 s1, 0
	s_lshl_b64 s[0:1], s[0:1], 2
	s_add_u32 s0, s38, s0
	s_addc_u32 s1, s39, s1
	v_mov_b32_e32 v2, 1
	v_mov_b64_e32 v[0:1], s[0:1]
	s_waitcnt vmcnt(0) lgkmcnt(0)
	buffer_inv sc1
	s_waitcnt vmcnt(0)

.LBB0_457:
	s_or_b64 exec, exec, s[4:5]
	s_add_i32 s48, s24, 0x900
	s_lshl_b64 s[4:5], s[48:49], 2
	s_add_u32 s4, s38, s4
	s_addc_u32 s5, s39, s5
	v_mov_b64_e32 v[2:3], s[4:5]
	v_mov_b32_e32 v0, 1
	s_waitcnt vmcnt(0) lgkmcnt(0)
	buffer_inv sc1
	s_waitcnt vmcnt(0)

.LBB0_631:
	s_or_b64 exec, exec, s[8:9]
	s_add_i32 s48, s28, 0x900
	s_lshl_b64 s[8:9], s[48:49], 2
	s_add_u32 s6, s6, s8
	s_addc_u32 s7, s7, s9
	v_mov_b64_e32 v[2:3], s[6:7]
	v_mov_b32_e32 v0, 1
	s_waitcnt vmcnt(0) lgkmcnt(0)
	buffer_inv sc1
	s_waitcnt vmcnt(0)

.LBB0_1359:
	s_or_b64 exec, exec, s[10:11]
	s_add_i32 s48, s30, 0x900
	s_lshl_b64 s[10:11], s[48:49], 2
	s_add_u32 s6, s6, s10
	s_addc_u32 s7, s7, s11
	v_mov_b64_e32 v[2:3], s[6:7]
	v_mov_b32_e32 v0, 1
	s_waitcnt vmcnt(0) lgkmcnt(0)
	buffer_inv sc1
	s_waitcnt vmcnt(0)

.LBB0_1770:
	s_or_b64 exec, exec, s[4:5]
	s_add_i32 s48, s26, 0x900
	s_lshl_b64 s[4:5], s[48:49], 2
	s_add_u32 s4, s38, s4
	s_addc_u32 s5, s39, s5
	v_mov_b64_e32 v[2:3], s[4:5]
	v_mov_b32_e32 v0, 1
	s_waitcnt vmcnt(0) lgkmcnt(0)
	buffer_inv sc1
	s_waitcnt vmcnt(0)
